# MLA loop: 4 LDS stages, one workgroup barrier per two key tiles (was one per tile)
# speedup vs baseline: 1.0069x; 1.0069x over previous
; #define LDS_BARRIER() asm volatile("s_waitcnt lgkmcnt(0)\n\ts_barrier" ::: "memory")
; template <int MODE>
; DI void attn_item(const Params& p, int layer, int bh, int qb, char* lds) {
;     ...
;   u32x4 rkA[KCH], rvA[1], rkB[KCH], rvB[1];
;   const __amdgpu_buffer_rsrc_t krsrc = __builtin_amdgcn_make_buffer_rsrc((void*)Kg, 0, S * KSTRG * 2, 0x00027000);
;   const __amdgpu_buffer_rsrc_t vrsrc = __builtin_amdgcn_make_buffer_rsrc((void*)Vg, 0, S * VSTRG * 2, 0x00027000);
;   auto gload = [&](int kt, u32x4 (&rk)[KCH], u32x4 (&rv)[1]) {
;     const int ksoff = kt * (64 * KSTRG * 2), vsoff = kt * (64 * VSTRG * 2);
; #pragma unroll
;     for (int i = 0; i < KCH; ++i) if (tid + NTHR * i < KCHUNKS) rk[i] = __builtin_amdgcn_raw_buffer_load_b128(krsrc, tid * 16 + NTHR * 16 * i, ksoff, 0);
;     rv[0] = __builtin_amdgcn_raw_buffer_load_b128(vrsrc, tid * 16, vsoff, 0);
;   };
;   auto lstore = [&](int st, const u32x4 (&rk)[KCH], const u32x4 (&rv)[1]) {
;     char* Ks = stage0 + st * STAGE;
; #pragma unroll
;     for (int i = 0; i < KCH; ++i) { int c = tid + NTHR * i, row = c / KCPR, ch = c % KCPR; if (c < KCHUNKS) *(u32x4*)(Ks + row * KSTR + ch * 16) = rk[i]; }
;     { int row = tid >> 3, ch = tid & 7; *(u32x4*)(Ks + KBYTES + row * VSTR + ch * 16) = rv[0]; }
;   };
;     ...
;   __syncthreads();
;   gload(kt0, rkA, rvA); lstore(0, rkA, rvA);
;   if (nt > 1) gload(kt0 + 1, rkB, rvB);
;   LDS_BARRIER();
.LBB0_403:
	s_ashr_i32 s5, s60, 5
	s_and_b32 s4, s60, 7
	s_and_b32 s5, s5, -8
	v_mov_b32_e32 v14, v184
	s_or_b32 s4, s5, s4
	s_lshl_b32 s5, s60, 5
	s_waitcnt vmcnt(0)
	v_ashrrev_i32_e32 v0, 1, v14
	s_and_b32 s5, s5, 0x1f00
	v_and_b32_e32 v0, 0xffffffe0, v0
	v_add_u32_e32 v186, s5, v0
	s_mul_hi_i32 s5, s4, 0x2aaaaaab
	s_lshr_b32 s6, s5, 31
	s_add_i32 s10, s5, s6
	s_mul_i32 s5, s10, 6
	s_sub_i32 s52, s4, s5
	s_mul_i32 s6, s10, 0x900000
	v_readlane_b32 s8, v254, 45
	s_mul_hi_i32 s5, s10, 0x900000
	v_readlane_b32 s9, v254, 46
	s_add_u32 s8, s8, s6
	s_mul_i32 s6, s52, 0x60
	s_addc_u32 s5, s9, s5
	s_ashr_i32 s7, s6, 31
	s_lshl_b64 s[6:7], s[6:7], 1
	s_add_u32 s6, s8, s6
	v_and_b32_e32 v204, 31, v14
	s_addc_u32 s7, s5, s7
	v_bfe_u32 v15, v14, 5, 1
	v_or_b32_e32 v2, v186, v204
	v_mov_b64_e32 v[0:1], s[6:7]
	s_movk_i32 s5, 0x480
	v_mad_i64_i32 v[0:1], s[6:7], v2, s5, v[0:1]
	v_lshlrev_b32_e32 v16, 4, v15
	v_mov_b32_e32 v17, v5
	v_lshl_add_u64 v[0:1], v[0:1], 0, v[16:17]
	global_load_dwordx4 v[104:107], v[0:1], off
	global_load_dwordx4 v[108:111], v[0:1], off offset:32
	global_load_dwordx4 v[112:115], v[0:1], off offset:64
	global_load_dwordx4 v[116:119], v[0:1], off offset:96
	global_load_dwordx4 v[120:123], v[0:1], off offset:128
	global_load_dwordx4 v[124:127], v[0:1], off offset:160
	s_ashr_i32 s5, s4, 31
	s_mul_hi_i32 s6, s4, 0x180000
	s_mul_i32 s7, s4, 0x180000
	s_lshl_b64 s[4:5], s[4:5], 20
	s_add_u32 s12, s68, s4
	s_addc_u32 s11, s69, s5
	s_add_u32 s20, s66, s7
	s_addc_u32 s4, s67, s6
	s_and_b32 s21, s4, 0xffff
	s_movk_i32 s4, 0x300
	v_cmp_gt_i32_e64 s[4:5], s4, v14
	v_lshlrev_b32_e32 v187, 4, v14
	v_mov_b32_e32 v100, 0
	v_mov_b32_e32 v96, 0
	v_mov_b32_e32 v97, 0
	v_mov_b32_e32 v98, 0
	v_mov_b32_e32 v99, 0
	s_barrier
	s_and_b32 s13, s11, 0xffff
	s_ashr_i32 s11, s10, 31
	s_mov_b32 s23, s15
	v_bfe_u32 v206, v184, 5, 1
	v_lshlrev_b32_e32 v206, 2, v206
	v_and_b32_e32 v196, 31, v184
	v_bfe_u32 v197, v184, 5, 1
	v_mov_b32_e32 v199, 208
	v_mul_u32_u24_e32 v200, v196, v199
	v_lshl_add_u32 v200, v197, 4, v200
	v_bfe_u32 v199, v184, 2, 2
	v_lshl_add_u32 v199, v197, 2, v199
	v_mov_b32_e32 v208, 192
	v_mul_u32_u24_e32 v201, v199, v208
	v_bfe_u32 v199, v184, 4, 1
	v_lshl_add_u32 v201, v199, 5, v201
	v_and_b32_e32 v199, 3, v184
	v_lshl_add_u32 v201, v199, 3, v201
	v_mov_b32_e32 v208, 0xaaab
	v_mul_u32_u24_e32 v196, v184, v208
	v_lshrrev_b32_e32 v196, 19, v196
	v_mul_u32_u24_e32 v197, 12, v196
	v_sub_u32_e32 v197, v184, v197
	v_mov_b32_e32 v199, 208
	v_mul_u32_u24_e32 v202, v196, v199
	v_lshl_add_u32 v202, v197, 4, v202
	v_lshrrev_b32_e32 v196, 1, v184
	v_add_u32_e32 v196, 0x200, v196
	v_mul_u32_u24_e32 v197, v196, v208
	v_lshrrev_b32_e32 v197, 19, v197
	v_mul_u32_u24_e32 v209, 12, v197
	v_sub_u32_e32 v196, v196, v209
	v_mul_u32_u24_e32 v203, v197, v199
	v_lshl_add_u32 v203, v196, 4, v203
	v_and_b32_e32 v196, 1, v184
	v_lshl_add_u32 v203, v196, 3, v203
	v_lshrrev_b32_e32 v196, 3, v184
	v_mov_b32_e32 v199, 192
	v_mul_u32_u24_e32 v207, v196, v199
	v_and_b32_e32 v196, 7, v184
	v_lshl_add_u32 v207, v196, 4, v207
	v_add_u32_e32 v248, 51200, v200
	v_add_u32_e32 v249, 51200, v201
	v_add_u32_e32 v250, 51200, v202
	v_add_u32_e32 v251, 51200, v203
	v_add_u32_e32 v194, 51200, v207
	v_lshlrev_b32_e32 v187, 4, v184
	v_lshlrev_b32_e32 v205, 3, v184
	v_add_u32_e32 v205, 0x2000, v205
	v_bfe_u32 v197, v184, 5, 1
	v_cmp_eq_u32_e64 s[8:9], 0, v197
	v_mov_b32_e32 v196, 0x3f803f80
	s_nop 0
	v_cndmask_b32_e64 v240, 0, v196, s[8:9]
	v_mov_b32_e32 v241, 0
	v_mov_b32_e32 v245, 0
	v_mov_b32_e32 v242, 0
	v_mov_b32_e32 v246, 0
	v_mov_b32_e32 v243, 0
	v_mov_b32_e32 v247, 0
	buffer_load_dwordx4 v[64:67], v187, s[20:23], 0 offen
	buffer_load_dwordx2 v[68:69], v205, s[20:23], 0 offen
	buffer_load_dwordx4 v[72:75], v187, s[12:15], 0 offen
	s_mov_b32 s62, 0x3000
	buffer_load_dwordx4 v[76:79], v187, s[20:23], s62 offen
	buffer_load_dwordx2 v[80:81], v205, s[20:23], s62 offen
	s_mov_b32 s62, 0x6000
	buffer_load_dwordx4 v[82:85], v187, s[20:23], s62 offen
	buffer_load_dwordx2 v[86:87], v205, s[20:23], s62 offen
	s_mov_b32 s29, 0x2000
	buffer_load_dwordx4 v[88:91], v187, s[12:15], s29 offen
	s_waitcnt vmcnt(0)
	ds_write_b128 v202, v[64:67] offset:2048
	ds_write_b64 v203, v[68:69] offset:2048
	ds_write_b128 v202, v[76:79] offset:27648
	ds_write_b64 v203, v[80:81] offset:27648
	ds_write_b128 v250, v[82:85] offset:2048
	ds_write_b64 v251, v[86:87] offset:2048
	ds_write_b128 v207, v[72:75] offset:15360
	ds_write_b128 v207, v[88:91] offset:40960
	s_mov_b32 s62, 0x9000
	buffer_load_dwordx4 v[96:99], v187, s[20:23], s62 offen
	buffer_load_dwordx2 v[100:101], v205, s[20:23], s62 offen
	s_mov_b32 s29, 0x4000
	buffer_load_dwordx4 v[188:191], v187, s[12:15], s29 offen
	s_mov_b32 s62, 0xc000
	buffer_load_dwordx4 v[230:233], v187, s[20:23], s62 offen
	buffer_load_dwordx2 v[234:235], v205, s[20:23], s62 offen
	s_mov_b32 s29, 0x6000
	buffer_load_dwordx4 v[236:239], v187, s[12:15], s29 offen
	s_mov_b32 s62, 0xf000
	s_mov_b32 s29, 0x8000
	s_waitcnt lgkmcnt(0)
	s_barrier
; #define MFMA(a, b, c) __builtin_amdgcn_mfma_f32_32x32x16_bf16((a), (b), (c), 0, 0, 0)
; template <int MODE>
; DI void attn_item(const Params& p, int layer, int bh, int qb, char* lds) {
;     ...
;         for (int sub = 0; sub < 2; ++sub) {
; #pragma unroll
;           for (int st = 0; st < QS; ++st) {
;             bf16x8 kf = *(const bf16x8*)(Ks + (32 * sub + l32) * KSTR + ((mp * QS + st) * 16 + hh * 8) * 2);
;             if (st == 0) s[sub] = MFMA(kf, qf[mp][st], c0tile); else s[sub] = MFMA(kf, qf[mp][st], s[sub]);
;           }
;         }
;         __builtin_amdgcn_iglp_opt(1);
;         __builtin_amdgcn_s_setprio(0);
;         if (NMAP == 1) {
;           lds_s16x4* vb = (lds_s16x4*)(Ks + KBYTES + vlane);
; #pragma unroll
;           for (int i = 0; i < 16; ++i) {
;             const int sub_ = i >> 3, ks_ = (i >> 2) & 1, dt_ = (i >> 1) & 1, g_ = i & 1;
;             vpre[i] = __builtin_amdgcn_ds_read_tr16_b64_v4i16(vb + ((32 * sub_ + 16 * ks_ + 8 * g_) * VSTR + 64 * dt_) / 8);
;           }
;           __builtin_amdgcn_sched_barrier(0);
;         }
;         if (MODE != 0 && !far) {
; #pragma unroll
;           for (int sub = 0; sub < 2; ++sub)
; #pragma unroll
;             for (int r = 0; r < 16; ++r) s[sub][r] += brow[32 * sub + (r & 3) + 8 * (r >> 2)];
;         }
;         const bool first = (MODE != 2) && (t == 0) && (mp == 0);
;         auto rebase = [&]() {
;           float mx = fmaxf(fmaxf(s[0][0], s[0][1]), s[0][2]);
; #pragma unroll
;           for (int r = 3; r < 15; r += 2) mx = fmaxf(fmaxf(mx, s[0][r]), s[0][r + 1]);
;           mx = fmaxf(mx, s[0][15]);
; #pragma unroll
;           for (int r = 0; r < 16; r += 2) mx = fmaxf(fmaxf(mx, s[1][r]), s[1][r + 1]);
;           const float rm = xchg_max(mx);
;           float delta = first ? rm : fmaxf(rm, 0.f);
;           if (delta < -1e29f) delta = 0.f;
;           m += delta;
;           const float alpha = __builtin_amdgcn_exp2f(-delta);
; #pragma unroll
;           for (int mq = 0; mq < NMAP; ++mq) {
;             l[mq] *= alpha;
; #pragma unroll
;             for (int r = 0; r < 16; ++r) { O[mq][0][r] *= alpha; O[mq][1][r] *= alpha; }
;           }
; #pragma unroll
;           for (int r = 0; r < 16; ++r) { s[0][r] -= delta; s[1][r] -= delta; }
;           set_c0(cb - m);
	ds_read_b128 v[176:179], v200 offset:2048
	ds_read_b128 v[180:183], v200 offset:2080
	ds_read_b128 v[222:225], v200 offset:2112
	s_waitcnt lgkmcnt(2)
	v_mfma_f32_32x32x16_bf16 v[64:79], v[176:179], v[104:107], 0
	ds_read_b128 v[226:229], v200 offset:2144
	s_waitcnt lgkmcnt(2)
	v_mfma_f32_32x32x16_bf16 v[64:79], v[180:183], v[108:111], v[64:79]
	ds_read_b128 v[176:179], v200 offset:2176
	s_waitcnt lgkmcnt(2)
	v_mfma_f32_32x32x16_bf16 v[64:79], v[222:225], v[112:115], v[64:79]
	ds_read_b128 v[180:183], v200 offset:2208
	s_waitcnt lgkmcnt(2)
	v_mfma_f32_32x32x16_bf16 v[64:79], v[226:229], v[116:119], v[64:79]
	ds_read_b128 v[222:225], v200 offset:8704
	s_waitcnt lgkmcnt(2)
	v_mfma_f32_32x32x16_bf16 v[64:79], v[176:179], v[120:123], v[64:79]
	ds_read_b128 v[226:229], v200 offset:8736
	s_waitcnt lgkmcnt(2)
	v_mfma_f32_32x32x16_bf16 v[64:79], v[180:183], v[124:127], v[64:79]
	ds_read_b128 v[176:179], v200 offset:8768
	s_waitcnt lgkmcnt(2)
	v_mfma_f32_32x32x16_bf16 v[80:95], v[222:225], v[104:107], 0
	ds_read_b128 v[180:183], v200 offset:8800
	s_waitcnt lgkmcnt(2)
	v_mfma_f32_32x32x16_bf16 v[80:95], v[226:229], v[108:111], v[80:95]
	ds_read_b128 v[222:225], v200 offset:8832
	s_waitcnt lgkmcnt(2)
	v_mfma_f32_32x32x16_bf16 v[80:95], v[176:179], v[112:115], v[80:95]
	ds_read_b128 v[226:229], v200 offset:8864
	s_waitcnt lgkmcnt(2)
	v_mfma_f32_32x32x16_bf16 v[80:95], v[180:183], v[116:119], v[80:95]
	s_waitcnt lgkmcnt(1)
	v_mfma_f32_32x32x16_bf16 v[80:95], v[222:225], v[120:123], v[80:95]
	s_waitcnt lgkmcnt(0)
	v_mfma_f32_32x32x16_bf16 v[80:95], v[226:229], v[124:127], v[80:95]
	v_mov_b32_e32 v16, 0
	v_mov_b32_e32 v32, 0
	v_mov_b32_e32 v17, 0
	v_mov_b32_e32 v33, 0
	v_mov_b32_e32 v18, 0
	v_mov_b32_e32 v34, 0
	v_mov_b32_e32 v19, 0
	v_mov_b32_e32 v35, 0
	v_mov_b32_e32 v20, 0
	v_mov_b32_e32 v36, 0
	v_mov_b32_e32 v21, 0
	v_mov_b32_e32 v37, 0
	v_mov_b32_e32 v22, 0
	v_mov_b32_e32 v38, 0
	v_mov_b32_e32 v23, 0
	v_mov_b32_e32 v39, 0
	v_mov_b32_e32 v24, 0
	v_mov_b32_e32 v40, 0
	v_mov_b32_e32 v25, 0
	v_mov_b32_e32 v41, 0
	v_mov_b32_e32 v26, 0
	v_mov_b32_e32 v42, 0
	v_mov_b32_e32 v27, 0
	v_mov_b32_e32 v43, 0
	v_mov_b32_e32 v28, 0
	v_mov_b32_e32 v44, 0
	v_mov_b32_e32 v29, 0
	v_mov_b32_e32 v45, 0
	v_mov_b32_e32 v30, 0
	v_mov_b32_e32 v46, 0
	v_mov_b32_e32 v31, 0
	v_mov_b32_e32 v47, 0
	v_mov_b32_e32 v192, 0
	v_mov_b32_e32 v193, 0
	s_waitcnt lgkmcnt(0)
	s_barrier
	v_max_f32_e32 v196, v64, v65
	v_max3_f32 v196, v196, v66, v67
	v_max3_f32 v196, v196, v68, v69
	v_max3_f32 v196, v196, v70, v71
	v_max3_f32 v196, v196, v72, v73
	v_max3_f32 v196, v196, v74, v75
	v_max3_f32 v196, v196, v76, v77
	v_max3_f32 v196, v196, v78, v79
	v_max3_f32 v196, v196, v80, v81
	v_max3_f32 v196, v196, v82, v83
	v_max3_f32 v196, v196, v84, v85
	v_max3_f32 v196, v196, v86, v87
	v_max3_f32 v196, v196, v88, v89
	v_max3_f32 v196, v196, v90, v91
	v_max3_f32 v196, v196, v92, v93
	v_max3_f32 v196, v196, v94, v95
	v_mov_b32_e32 v197, v196
	s_nop 1
	v_permlane32_swap_b32_e32 v196, v197
	v_max_f32_e32 v196, v196, v197
	s_mov_b32 s24, 0xefa18f08
	v_cmp_ngt_f32_e32 vcc, s24, v196
	s_nop 1
	v_cndmask_b32_e32 v198, 0, v196, vcc
	v_sub_f32_e32 v64, v64, v198
	v_sub_f32_e32 v65, v65, v198
	v_sub_f32_e32 v66, v66, v198
	v_sub_f32_e32 v67, v67, v198
	v_sub_f32_e32 v68, v68, v198
	v_sub_f32_e32 v69, v69, v198
	v_sub_f32_e32 v70, v70, v198
	v_sub_f32_e32 v71, v71, v198
	v_sub_f32_e32 v72, v72, v198
	v_sub_f32_e32 v73, v73, v198
	v_sub_f32_e32 v74, v74, v198
	v_sub_f32_e32 v75, v75, v198
	v_sub_f32_e32 v76, v76, v198
	v_sub_f32_e32 v77, v77, v198
	v_sub_f32_e32 v78, v78, v198
	v_sub_f32_e32 v79, v79, v198
	v_sub_f32_e32 v80, v80, v198
	v_sub_f32_e32 v81, v81, v198
	v_sub_f32_e32 v82, v82, v198
	v_sub_f32_e32 v83, v83, v198
	v_sub_f32_e32 v84, v84, v198
	v_sub_f32_e32 v85, v85, v198
	v_sub_f32_e32 v86, v86, v198
	v_sub_f32_e32 v87, v87, v198
	v_sub_f32_e32 v88, v88, v198
	v_sub_f32_e32 v89, v89, v198
	v_sub_f32_e32 v90, v90, v198
	v_sub_f32_e32 v91, v91, v198
	v_sub_f32_e32 v92, v92, v198
	v_sub_f32_e32 v93, v93, v198
	v_sub_f32_e32 v94, v94, v198
	v_sub_f32_e32 v95, v95, v198
	v_sub_f32_e32 v196, 0, v198
	v_bfe_u32 v197, v196, 16, 1
	v_add3_u32 v196, v196, v197, s45
	v_lshrrev_b32_e32 v197, 16, v196
	v_and_b32_e32 v196, 0xffff0000, v196
	v_sub_f32_e64 v196, -v198, v196
	v_bfe_u32 v199, v196, 16, 1
	v_add3_u32 v196, v196, v199, s45
	v_and_or_b32 v196, v196, s92, v197
	v_cndmask_b32_e64 v244, 0, v196, s[8:9]
	s_nop 1
	v_mfma_f32_32x32x16_bf16 v[48:63], v[240:243], v[244:247], 0
	s_mov_b32 s28, 0
; template <int MODE>
; DI void attn_item(const Params& p, int layer, int bh, int qb, char* lds) {
;     ...
;   auto gload = [&](int kt, u32x4 (&rk)[KCH], u32x4 (&rv)[1]) {
;     const int ksoff = kt * (64 * KSTRG * 2), vsoff = kt * (64 * VSTRG * 2);
; #pragma unroll
;     for (int i = 0; i < KCH; ++i) if (tid + NTHR * i < KCHUNKS) rk[i] = __builtin_amdgcn_raw_buffer_load_b128(krsrc, tid * 16 + NTHR * 16 * i, ksoff, 0);
;     rv[0] = __builtin_amdgcn_raw_buffer_load_b128(vrsrc, tid * 16, vsoff, 0);
;   };
;   auto lstore = [&](int st, const u32x4 (&rk)[KCH], const u32x4 (&rv)[1]) {
;     char* Ks = stage0 + st * STAGE;
; #pragma unroll
;     for (int i = 0; i < KCH; ++i) { int c = tid + NTHR * i, row = c / KCPR, ch = c % KCPR; if (c < KCHUNKS) *(u32x4*)(Ks + row * KSTR + ch * 16) = rk[i]; }
;     { int row = tid >> 3, ch = tid & 7; *(u32x4*)(Ks + KBYTES + row * VSTR + ch * 16) = rv[0]; }
;   };
;     ...
; #pragma unroll
;           for (int st = 0; st < QS; ++st) {
;             bf16x8 kf = *(const bf16x8*)(Ks + (32 * sub + l32) * KSTR + ((mp * QS + st) * 16 + hh * 8) * 2);
;             if (st == 0) s[sub] = MFMA(kf, qf[mp][st], c0tile); else s[sub] = MFMA(kf, qf[mp][st], s[sub]);
;           }
;         }
;         __builtin_amdgcn_iglp_opt(1);
;         __builtin_amdgcn_s_setprio(0);
;         if (NMAP == 1) {
;           lds_s16x4* vb = (lds_s16x4*)(Ks + KBYTES + vlane);
; #pragma unroll
;           for (int i = 0; i < 16; ++i) {
;             const int sub_ = i >> 3, ks_ = (i >> 2) & 1, dt_ = (i >> 1) & 1, g_ = i & 1;
;             vpre[i] = __builtin_amdgcn_ds_read_tr16_b64_v4i16(vb + ((32 * sub_ + 16 * ks_ + 8 * g_) * VSTR + 64 * dt_) / 8);
;           }
;           __builtin_amdgcn_sched_barrier(0);
;         }
;         if (MODE != 0 && !far) {
; #pragma unroll
;           for (int sub = 0; sub < 2; ++sub)
; #pragma unroll
;             for (int r = 0; r < 16; ++r) s[sub][r] += brow[32 * sub + (r & 3) + 8 * (r >> 2)];
;         }
;         const bool first = (MODE != 2) && (t == 0) && (mp == 0);
;         auto rebase = [&]() {
;           float mx = fmaxf(fmaxf(s[0][0], s[0][1]), s[0][2]);
; #pragma unroll
;           for (int r = 3; r < 15; r += 2) mx = fmaxf(fmaxf(mx, s[0][r]), s[0][r + 1]);
;           mx = fmaxf(mx, s[0][15]);
; #pragma unroll
;           for (int r = 0; r < 16; r += 2) mx = fmaxf(fmaxf(mx, s[1][r]), s[1][r + 1]);
.Lmla_loop:
	ds_read_b128 v[176:179], v200 offset:27648
	ds_read_b128 v[180:183], v200 offset:27680
	ds_read_b128 v[222:225], v200 offset:27712
	s_waitcnt vmcnt(0)
	ds_write_b128 v250, v[96:99] offset:27648
	ds_write_b64 v251, v[100:101] offset:27648
	ds_write_b128 v194, v[188:191] offset:15360
	ds_write_b128 v202, v[230:233] offset:2048
	ds_write_b64 v203, v[234:235] offset:2048
	ds_write_b128 v194, v[236:239] offset:40960
	buffer_load_dwordx4 v[96:99], v187, s[20:23], s62 offen
	buffer_load_dwordx2 v[100:101], v205, s[20:23], s62 offen
	buffer_load_dwordx4 v[188:191], v187, s[12:15], s29 offen
	s_add_u32 s62, s62, 0x3000
	s_add_u32 s29, s29, 0x2000
	buffer_load_dwordx4 v[230:233], v187, s[20:23], s62 offen
	buffer_load_dwordx2 v[234:235], v205, s[20:23], s62 offen
	buffer_load_dwordx4 v[236:239], v187, s[12:15], s29 offen
	s_add_u32 s62, s62, 0x3000
	s_add_u32 s29, s29, 0x2000
	v_exp_f32_e32 v0, v64
	v_exp_f32_e32 v1, v65
	v_exp_f32_e32 v2, v66
	v_exp_f32_e32 v3, v67
	v_add_f32_e32 v10, v0, v1
	v_cvt_pk_bf16_f32 v160, v0, v1
	s_waitcnt lgkmcnt(8)
	v_mfma_f32_32x32x16_bf16 v[128:143], v[176:179], v[104:107], v[48:63]
	ds_read_b128 v[226:229], v200 offset:27744
	s_waitcnt lgkmcnt(8)
	v_mfma_f32_32x32x16_bf16 v[128:143], v[180:183], v[108:111], v[128:143]
	ds_read_b64_tr_b16 v[176:177], v201 offset:15360
	ds_read_b64_tr_b16 v[178:179], v201 offset:16896
	v_add_f32_e32 v10, v10, v2
	v_add_f32_e32 v10, v10, v3
	v_cvt_pk_bf16_f32 v161, v2, v3
	s_waitcnt lgkmcnt(9)
	v_mfma_f32_32x32x16_bf16 v[128:143], v[222:225], v[112:115], v[128:143]
	ds_read_b64_tr_b16 v[180:181], v201 offset:15424
	ds_read_b64_tr_b16 v[182:183], v201 offset:16960
	v_exp_f32_e32 v6, v68
	v_exp_f32_e32 v7, v69
	v_exp_f32_e32 v8, v70
	v_exp_f32_e32 v9, v71
	v_add_f32_e32 v10, v10, v6
	s_waitcnt lgkmcnt(4)
	v_mfma_f32_32x32x16_bf16 v[128:143], v[226:229], v[116:119], v[128:143]
	ds_read_b128 v[222:225], v200 offset:27776
	v_add_f32_e32 v10, v10, v7
	v_cvt_pk_bf16_f32 v162, v6, v7
	v_add_f32_e32 v10, v10, v8
	v_add_f32_e32 v10, v10, v9
	v_cvt_pk_bf16_f32 v163, v8, v9
	s_waitcnt lgkmcnt(3)
	s_nop 0
	v_mfma_f32_32x32x16_bf16 v[32:47], v[176:179], v[160:163], v[32:47]
	ds_read_b128 v[226:229], v200 offset:27808
	v_exp_f32_e32 v0, v72
	v_exp_f32_e32 v1, v73
	v_exp_f32_e32 v2, v74
	s_waitcnt lgkmcnt(2)
	v_mfma_f32_32x32x16_bf16 v[16:31], v[180:183], v[160:163], v[16:31]
	ds_read_b128 v[176:179], v200 offset:34304
	v_exp_f32_e32 v3, v75
	v_add_f32_e32 v11, v0, v1
	v_cvt_pk_bf16_f32 v164, v0, v1
	v_add_f32_e32 v11, v11, v2
	s_waitcnt lgkmcnt(2)
	v_mfma_f32_32x32x16_bf16 v[128:143], v[222:225], v[120:123], v[128:143]
	ds_read_b64_tr_b16 v[180:181], v201 offset:18432
	ds_read_b64_tr_b16 v[182:183], v201 offset:19968
	v_add_f32_e32 v11, v11, v3
	v_cvt_pk_bf16_f32 v165, v2, v3
	v_exp_f32_e32 v6, v76
	v_exp_f32_e32 v7, v77
	s_waitcnt lgkmcnt(3)
	v_mfma_f32_32x32x16_bf16 v[128:143], v[226:229], v[124:127], v[128:143]
	ds_read_b64_tr_b16 v[222:223], v201 offset:18496
	ds_read_b64_tr_b16 v[224:225], v201 offset:20032
	v_exp_f32_e32 v8, v78
	v_exp_f32_e32 v9, v79
	v_add_f32_e32 v11, v11, v6
	v_add_f32_e32 v11, v11, v7
	s_waitcnt lgkmcnt(4)
	v_mfma_f32_32x32x16_bf16 v[144:159], v[176:179], v[104:107], v[48:63]
	ds_read_b128 v[226:229], v200 offset:34336
	v_cvt_pk_bf16_f32 v166, v6, v7
	v_add_f32_e32 v11, v11, v8
	v_add_f32_e32 v11, v11, v9
	v_cvt_pk_bf16_f32 v167, v8, v9
	s_waitcnt lgkmcnt(3)
	s_nop 0
	v_mfma_f32_32x32x16_bf16 v[32:47], v[180:183], v[164:167], v[32:47]
	ds_read_b128 v[176:179], v200 offset:34368
	v_exp_f32_e32 v0, v80
	v_exp_f32_e32 v1, v81
	v_exp_f32_e32 v2, v82
	s_waitcnt lgkmcnt(2)
	v_mfma_f32_32x32x16_bf16 v[16:31], v[222:225], v[164:167], v[16:31]
	ds_read_b128 v[180:183], v200 offset:34400
	v_exp_f32_e32 v3, v83
	v_add_f32_e32 v12, v0, v1
	v_cvt_pk_bf16_f32 v168, v0, v1
	v_add_f32_e32 v12, v12, v2
	s_waitcnt lgkmcnt(2)
	v_mfma_f32_32x32x16_bf16 v[144:159], v[226:229], v[108:111], v[144:159]
	ds_read_b64_tr_b16 v[222:223], v201 offset:21504
	ds_read_b64_tr_b16 v[224:225], v201 offset:23040
	v_add_f32_e32 v12, v12, v3
	v_cvt_pk_bf16_f32 v169, v2, v3
	v_exp_f32_e32 v6, v84
	v_exp_f32_e32 v7, v85
	s_waitcnt lgkmcnt(3)
	v_mfma_f32_32x32x16_bf16 v[144:159], v[176:179], v[112:115], v[144:159]
	ds_read_b64_tr_b16 v[226:227], v201 offset:21568
	ds_read_b64_tr_b16 v[228:229], v201 offset:23104
	v_exp_f32_e32 v8, v86
	v_exp_f32_e32 v9, v87
	v_add_f32_e32 v12, v12, v6
	v_add_f32_e32 v12, v12, v7
	s_waitcnt lgkmcnt(4)
	v_mfma_f32_32x32x16_bf16 v[144:159], v[180:183], v[116:119], v[144:159]
	ds_read_b128 v[176:179], v200 offset:34432
	v_cvt_pk_bf16_f32 v170, v6, v7
	v_add_f32_e32 v12, v12, v8
	v_add_f32_e32 v12, v12, v9
	v_cvt_pk_bf16_f32 v171, v8, v9
	s_waitcnt lgkmcnt(3)
	s_nop 0
	v_mfma_f32_32x32x16_bf16 v[32:47], v[222:225], v[168:171], v[32:47]
	ds_read_b128 v[180:183], v200 offset:34464
	v_exp_f32_e32 v0, v88
	v_exp_f32_e32 v1, v89
	v_exp_f32_e32 v2, v90
	v_exp_f32_e32 v3, v91
	s_waitcnt lgkmcnt(2)
	v_mfma_f32_32x32x16_bf16 v[16:31], v[226:229], v[168:171], v[16:31]
	ds_read_b64_tr_b16 v[222:223], v201 offset:24576
	ds_read_b64_tr_b16 v[224:225], v201 offset:26112
	v_add_f32_e32 v13, v0, v1
	v_cvt_pk_bf16_f32 v172, v0, v1
	v_add_f32_e32 v13, v13, v2
	v_add_f32_e32 v13, v13, v3
	v_cvt_pk_bf16_f32 v173, v2, v3
	s_waitcnt lgkmcnt(3)
	v_mfma_f32_32x32x16_bf16 v[144:159], v[176:179], v[120:123], v[144:159]
	ds_read_b64_tr_b16 v[226:227], v201 offset:24640
	ds_read_b64_tr_b16 v[228:229], v201 offset:26176
	v_exp_f32_e32 v6, v92
	v_exp_f32_e32 v7, v93
	v_exp_f32_e32 v8, v94
	v_exp_f32_e32 v9, v95
	v_add_f32_e32 v13, v13, v6
	s_waitcnt lgkmcnt(4)
; template <int MODE>
; DI void attn_item(const Params& p, int layer, int bh, int qb, char* lds) {
;     ...
; #pragma unroll
;           for (int st = 0; st < QS; ++st) {
;             bf16x8 kf = *(const bf16x8*)(Ks + (32 * sub + l32) * KSTR + ((mp * QS + st) * 16 + hh * 8) * 2);
;             if (st == 0) s[sub] = MFMA(kf, qf[mp][st], c0tile); else s[sub] = MFMA(kf, qf[mp][st], s[sub]);
;           }
;         }
;         __builtin_amdgcn_iglp_opt(1);
;         __builtin_amdgcn_s_setprio(0);
;         if (NMAP == 1) {
;           lds_s16x4* vb = (lds_s16x4*)(Ks + KBYTES + vlane);
; #pragma unroll
;           for (int i = 0; i < 16; ++i) {
;             const int sub_ = i >> 3, ks_ = (i >> 2) & 1, dt_ = (i >> 1) & 1, g_ = i & 1;
;             vpre[i] = __builtin_amdgcn_ds_read_tr16_b64_v4i16(vb + ((32 * sub_ + 16 * ks_ + 8 * g_) * VSTR + 64 * dt_) / 8);
;           }
;           __builtin_amdgcn_sched_barrier(0);
;         }
;         if (MODE != 0 && !far) {
; #pragma unroll
;           for (int sub = 0; sub < 2; ++sub)
; #pragma unroll
;             for (int r = 0; r < 16; ++r) s[sub][r] += brow[32 * sub + (r & 3) + 8 * (r >> 2)];
;         }
;         const bool first = (MODE != 2) && (t == 0) && (mp == 0);
;         auto rebase = [&]() {
;           float mx = fmaxf(fmaxf(s[0][0], s[0][1]), s[0][2]);
; #pragma unroll
;           for (int r = 3; r < 15; r += 2) mx = fmaxf(fmaxf(mx, s[0][r]), s[0][r + 1]);
;           mx = fmaxf(mx, s[0][15]);
; #pragma unroll
;           for (int r = 0; r < 16; r += 2) mx = fmaxf(fmaxf(mx, s[1][r]), s[1][r + 1]);
;           const float rm = xchg_max(mx);
;           float delta = first ? rm : fmaxf(rm, 0.f);
;           if (delta < -1e29f) delta = 0.f;
;           m += delta;
;           const float alpha = __builtin_amdgcn_exp2f(-delta);
; #pragma unroll
;           for (int mq = 0; mq < NMAP; ++mq) {
;             l[mq] *= alpha;
; #pragma unroll
;             for (int r = 0; r < 16; ++r) { O[mq][0][r] *= alpha; O[mq][1][r] *= alpha; }
;           }
; #pragma unroll
;           for (int r = 0; r < 16; ++r) { s[0][r] -= delta; s[1][r] -= delta; }
;           set_c0(cb - m);
;         };
;         float ps;
;         auto smpass = [&]() {
;           ps = 0.f;
; #pragma unroll
;           for (int sub = 0; sub < 2; ++sub)
; #pragma unroll
;             for (int ks = 0; ks < 2; ++ks)
; #pragma unroll
	v_mfma_f32_32x32x16_bf16 v[144:159], v[180:183], v[124:127], v[144:159]
	v_add_f32_e32 v13, v13, v7
	v_cvt_pk_bf16_f32 v174, v6, v7
	v_add_f32_e32 v13, v13, v8
	v_add_f32_e32 v13, v13, v9
	v_cvt_pk_bf16_f32 v175, v8, v9
	s_waitcnt lgkmcnt(2)
	s_nop 0
	v_mfma_f32_32x32x16_bf16 v[32:47], v[222:225], v[172:175], v[32:47]
	s_waitcnt lgkmcnt(0)
	v_mfma_f32_32x32x16_bf16 v[16:31], v[226:229], v[172:175], v[16:31]
	v_add_f32_e32 v10, v10, v11
	v_add_f32_e32 v12, v12, v13
	v_add_f32_e32 v10, v10, v12
	v_add_f32_e32 v192, v192, v10
	v_max_f32_e32 v193, v193, v10
	ds_read_b128 v[176:179], v248 offset:2048
	ds_read_b128 v[180:183], v248 offset:2080
	ds_read_b128 v[222:225], v248 offset:2112
	v_exp_f32_e32 v0, v128
	v_exp_f32_e32 v1, v129
	v_exp_f32_e32 v2, v130
	v_exp_f32_e32 v3, v131
	v_add_f32_e32 v10, v0, v1
	v_cvt_pk_bf16_f32 v160, v0, v1
	s_waitcnt lgkmcnt(2)
	v_mfma_f32_32x32x16_bf16 v[64:79], v[176:179], v[104:107], v[48:63]
	ds_read_b128 v[226:229], v248 offset:2144
	s_waitcnt lgkmcnt(2)
	v_mfma_f32_32x32x16_bf16 v[64:79], v[180:183], v[108:111], v[64:79]
	ds_read_b64_tr_b16 v[176:177], v201 offset:40960
	ds_read_b64_tr_b16 v[178:179], v201 offset:42496
	v_add_f32_e32 v10, v10, v2
	v_add_f32_e32 v10, v10, v3
	v_cvt_pk_bf16_f32 v161, v2, v3
	s_waitcnt lgkmcnt(3)
	v_mfma_f32_32x32x16_bf16 v[64:79], v[222:225], v[112:115], v[64:79]
	ds_read_b64_tr_b16 v[180:181], v201 offset:41024
	ds_read_b64_tr_b16 v[182:183], v201 offset:42560
	v_exp_f32_e32 v6, v132
	v_exp_f32_e32 v7, v133
	v_exp_f32_e32 v8, v134
	v_exp_f32_e32 v9, v135
	v_add_f32_e32 v10, v10, v6
	s_waitcnt lgkmcnt(4)
	v_mfma_f32_32x32x16_bf16 v[64:79], v[226:229], v[116:119], v[64:79]
	ds_read_b128 v[222:225], v248 offset:2176
	v_add_f32_e32 v10, v10, v7
	v_cvt_pk_bf16_f32 v162, v6, v7
	v_add_f32_e32 v10, v10, v8
	v_add_f32_e32 v10, v10, v9
	v_cvt_pk_bf16_f32 v163, v8, v9
	s_waitcnt lgkmcnt(3)
	s_nop 0
	v_mfma_f32_32x32x16_bf16 v[32:47], v[176:179], v[160:163], v[32:47]
	ds_read_b128 v[226:229], v248 offset:2208
	v_exp_f32_e32 v0, v136
	v_exp_f32_e32 v1, v137
	v_exp_f32_e32 v2, v138
	s_waitcnt lgkmcnt(2)
	v_mfma_f32_32x32x16_bf16 v[16:31], v[180:183], v[160:163], v[16:31]
	ds_read_b128 v[176:179], v248 offset:8704
	v_exp_f32_e32 v3, v139
	v_add_f32_e32 v11, v0, v1
	v_cvt_pk_bf16_f32 v164, v0, v1
	v_add_f32_e32 v11, v11, v2
	s_waitcnt lgkmcnt(2)
	v_mfma_f32_32x32x16_bf16 v[64:79], v[222:225], v[120:123], v[64:79]
	ds_read_b64_tr_b16 v[180:181], v201 offset:44032
	ds_read_b64_tr_b16 v[182:183], v201 offset:45568
	v_add_f32_e32 v11, v11, v3
	v_cvt_pk_bf16_f32 v165, v2, v3
	v_exp_f32_e32 v6, v140
	v_exp_f32_e32 v7, v141
	s_waitcnt lgkmcnt(3)
	v_mfma_f32_32x32x16_bf16 v[64:79], v[226:229], v[124:127], v[64:79]
	ds_read_b64_tr_b16 v[222:223], v201 offset:44096
	ds_read_b64_tr_b16 v[224:225], v201 offset:45632
	v_exp_f32_e32 v8, v142
	v_exp_f32_e32 v9, v143
	v_add_f32_e32 v11, v11, v6
	v_add_f32_e32 v11, v11, v7
	s_waitcnt lgkmcnt(4)
	v_mfma_f32_32x32x16_bf16 v[80:95], v[176:179], v[104:107], v[48:63]
	ds_read_b128 v[226:229], v248 offset:8736
	v_cvt_pk_bf16_f32 v166, v6, v7
	v_add_f32_e32 v11, v11, v8
	v_add_f32_e32 v11, v11, v9
	v_cvt_pk_bf16_f32 v167, v8, v9
	s_waitcnt lgkmcnt(3)
	s_nop 0
	v_mfma_f32_32x32x16_bf16 v[32:47], v[180:183], v[164:167], v[32:47]
	ds_read_b128 v[176:179], v248 offset:8768
	v_exp_f32_e32 v0, v144
	v_exp_f32_e32 v1, v145
	v_exp_f32_e32 v2, v146
	s_waitcnt lgkmcnt(2)
	v_mfma_f32_32x32x16_bf16 v[16:31], v[222:225], v[164:167], v[16:31]
	ds_read_b128 v[180:183], v248 offset:8800
	v_exp_f32_e32 v3, v147
	v_add_f32_e32 v12, v0, v1
	v_cvt_pk_bf16_f32 v168, v0, v1
	v_add_f32_e32 v12, v12, v2
	s_waitcnt lgkmcnt(2)
	v_mfma_f32_32x32x16_bf16 v[80:95], v[226:229], v[108:111], v[80:95]
	ds_read_b64_tr_b16 v[222:223], v201 offset:47104
	ds_read_b64_tr_b16 v[224:225], v201 offset:48640
	v_add_f32_e32 v12, v12, v3
	v_cvt_pk_bf16_f32 v169, v2, v3
	v_exp_f32_e32 v6, v148
	v_exp_f32_e32 v7, v149
	s_waitcnt lgkmcnt(3)
	v_mfma_f32_32x32x16_bf16 v[80:95], v[176:179], v[112:115], v[80:95]
	ds_read_b64_tr_b16 v[226:227], v201 offset:47168
	ds_read_b64_tr_b16 v[228:229], v201 offset:48704
	v_exp_f32_e32 v8, v150
	v_exp_f32_e32 v9, v151
	v_add_f32_e32 v12, v12, v6
	v_add_f32_e32 v12, v12, v7
	s_waitcnt lgkmcnt(4)
	v_mfma_f32_32x32x16_bf16 v[80:95], v[180:183], v[116:119], v[80:95]
	ds_read_b128 v[176:179], v248 offset:8832
	v_cvt_pk_bf16_f32 v170, v6, v7
	v_add_f32_e32 v12, v12, v8
	v_add_f32_e32 v12, v12, v9
	v_cvt_pk_bf16_f32 v171, v8, v9
	s_waitcnt lgkmcnt(3)
	s_nop 0
	v_mfma_f32_32x32x16_bf16 v[32:47], v[222:225], v[168:171], v[32:47]
	ds_read_b128 v[180:183], v248 offset:8864
	v_exp_f32_e32 v0, v152
	v_exp_f32_e32 v1, v153
	v_exp_f32_e32 v2, v154
	v_exp_f32_e32 v3, v155
	s_waitcnt lgkmcnt(2)
	v_mfma_f32_32x32x16_bf16 v[16:31], v[226:229], v[168:171], v[16:31]
	ds_read_b64_tr_b16 v[222:223], v201 offset:50176
	ds_read_b64_tr_b16 v[224:225], v201 offset:51712
	v_add_f32_e32 v13, v0, v1
	v_cvt_pk_bf16_f32 v172, v0, v1
	v_add_f32_e32 v13, v13, v2
	v_add_f32_e32 v13, v13, v3
	v_cvt_pk_bf16_f32 v173, v2, v3
	s_waitcnt lgkmcnt(3)
	v_mfma_f32_32x32x16_bf16 v[80:95], v[176:179], v[120:123], v[80:95]
	ds_read_b64_tr_b16 v[226:227], v201 offset:50240
	ds_read_b64_tr_b16 v[228:229], v201 offset:51776
	v_exp_f32_e32 v6, v156
	v_exp_f32_e32 v7, v157
	v_exp_f32_e32 v8, v158
	v_exp_f32_e32 v9, v159
	v_add_f32_e32 v13, v13, v6
	s_waitcnt lgkmcnt(4)
	v_mfma_f32_32x32x16_bf16 v[80:95], v[180:183], v[124:127], v[80:95]
	v_add_f32_e32 v13, v13, v7
	v_cvt_pk_bf16_f32 v174, v6, v7
	v_add_f32_e32 v13, v13, v8
	v_add_f32_e32 v13, v13, v9
	v_cvt_pk_bf16_f32 v175, v8, v9
	s_waitcnt lgkmcnt(2)
	s_nop 0
	v_mfma_f32_32x32x16_bf16 v[32:47], v[222:225], v[172:175], v[32:47]
	s_waitcnt lgkmcnt(0)
	v_mfma_f32_32x32x16_bf16 v[16:31], v[226:229], v[172:175], v[16:31]
	v_add_f32_e32 v10, v10, v11
	v_add_f32_e32 v12, v12, v13
	v_add_f32_e32 v10, v10, v12
	v_add_f32_e32 v192, v192, v10
	v_max_f32_e32 v193, v193, v10
	s_waitcnt lgkmcnt(0)
	s_barrier
; template <int MODE>
; DI void attn_item(const Params& p, int layer, int bh, int qb, char* lds) {
;     ...
;   auto gload = [&](int kt, u32x4 (&rk)[KCH], u32x4 (&rv)[1]) {
;     const int ksoff = kt * (64 * KSTRG * 2), vsoff = kt * (64 * VSTRG * 2);
; #pragma unroll
;     for (int i = 0; i < KCH; ++i) if (tid + NTHR * i < KCHUNKS) rk[i] = __builtin_amdgcn_raw_buffer_load_b128(krsrc, tid * 16 + NTHR * 16 * i, ksoff, 0);
;     rv[0] = __builtin_amdgcn_raw_buffer_load_b128(vrsrc, tid * 16, vsoff, 0);
;   };
;   auto lstore = [&](int st, const u32x4 (&rk)[KCH], const u32x4 (&rv)[1]) {
;     char* Ks = stage0 + st * STAGE;
; #pragma unroll
;     for (int i = 0; i < KCH; ++i) { int c = tid + NTHR * i, row = c / KCPR, ch = c % KCPR; if (c < KCHUNKS) *(u32x4*)(Ks + row * KSTR + ch * 16) = rk[i]; }
;     { int row = tid >> 3, ch = tid & 7; *(u32x4*)(Ks + KBYTES + row * VSTR + ch * 16) = rv[0]; }
;   };
;     ...
; #pragma unroll
;           for (int st = 0; st < QS; ++st) {
;             bf16x8 kf = *(const bf16x8*)(Ks + (32 * sub + l32) * KSTR + ((mp * QS + st) * 16 + hh * 8) * 2);
;             if (st == 0) s[sub] = MFMA(kf, qf[mp][st], c0tile); else s[sub] = MFMA(kf, qf[mp][st], s[sub]);
;           }
;         }
;         __builtin_amdgcn_iglp_opt(1);
;         __builtin_amdgcn_s_setprio(0);
;         if (NMAP == 1) {
;           lds_s16x4* vb = (lds_s16x4*)(Ks + KBYTES + vlane);
; #pragma unroll
;           for (int i = 0; i < 16; ++i) {
;             const int sub_ = i >> 3, ks_ = (i >> 2) & 1, dt_ = (i >> 1) & 1, g_ = i & 1;
;             vpre[i] = __builtin_amdgcn_ds_read_tr16_b64_v4i16(vb + ((32 * sub_ + 16 * ks_ + 8 * g_) * VSTR + 64 * dt_) / 8);
;           }
;           __builtin_amdgcn_sched_barrier(0);
;         }
;         if (MODE != 0 && !far) {
; #pragma unroll
;           for (int sub = 0; sub < 2; ++sub)
; #pragma unroll
;             for (int r = 0; r < 16; ++r) s[sub][r] += brow[32 * sub + (r & 3) + 8 * (r >> 2)];
;         }
;         const bool first = (MODE != 2) && (t == 0) && (mp == 0);
;         auto rebase = [&]() {
;           float mx = fmaxf(fmaxf(s[0][0], s[0][1]), s[0][2]);
; #pragma unroll
;           for (int r = 3; r < 15; r += 2) mx = fmaxf(fmaxf(mx, s[0][r]), s[0][r + 1]);
;           mx = fmaxf(mx, s[0][15]);
; #pragma unroll
;           for (int r = 0; r < 16; r += 2) mx = fmaxf(fmaxf(mx, s[1][r]), s[1][r + 1]);
	ds_read_b128 v[176:179], v248 offset:27648
	ds_read_b128 v[180:183], v248 offset:27680
	ds_read_b128 v[222:225], v248 offset:27712
	s_waitcnt vmcnt(0)
	ds_write_b128 v202, v[96:99] offset:27648
	ds_write_b64 v203, v[100:101] offset:27648
	ds_write_b128 v207, v[188:191] offset:15360
	ds_write_b128 v250, v[230:233] offset:2048
	ds_write_b64 v251, v[234:235] offset:2048
	ds_write_b128 v207, v[236:239] offset:40960
	buffer_load_dwordx4 v[96:99], v187, s[20:23], s62 offen
	buffer_load_dwordx2 v[100:101], v205, s[20:23], s62 offen
	buffer_load_dwordx4 v[188:191], v187, s[12:15], s29 offen
	s_add_u32 s62, s62, 0x3000
	s_add_u32 s29, s29, 0x2000
	buffer_load_dwordx4 v[230:233], v187, s[20:23], s62 offen
	buffer_load_dwordx2 v[234:235], v205, s[20:23], s62 offen
	buffer_load_dwordx4 v[236:239], v187, s[12:15], s29 offen
	s_add_u32 s62, s62, 0x3000
	s_add_u32 s29, s29, 0x2000
	v_exp_f32_e32 v0, v64
	v_exp_f32_e32 v1, v65
	v_exp_f32_e32 v2, v66
	v_exp_f32_e32 v3, v67
	v_add_f32_e32 v10, v0, v1
	v_cvt_pk_bf16_f32 v160, v0, v1
	s_waitcnt lgkmcnt(8)
	v_mfma_f32_32x32x16_bf16 v[128:143], v[176:179], v[104:107], v[48:63]
	ds_read_b128 v[226:229], v248 offset:27744
	s_waitcnt lgkmcnt(8)
	v_mfma_f32_32x32x16_bf16 v[128:143], v[180:183], v[108:111], v[128:143]
	ds_read_b64_tr_b16 v[176:177], v249 offset:15360
	ds_read_b64_tr_b16 v[178:179], v249 offset:16896
	v_add_f32_e32 v10, v10, v2
	v_add_f32_e32 v10, v10, v3
	v_cvt_pk_bf16_f32 v161, v2, v3
	s_waitcnt lgkmcnt(9)
	v_mfma_f32_32x32x16_bf16 v[128:143], v[222:225], v[112:115], v[128:143]
	ds_read_b64_tr_b16 v[180:181], v249 offset:15424
	ds_read_b64_tr_b16 v[182:183], v249 offset:16960
	v_exp_f32_e32 v6, v68
	v_exp_f32_e32 v7, v69
	v_exp_f32_e32 v8, v70
	v_exp_f32_e32 v9, v71
	v_add_f32_e32 v10, v10, v6
	s_waitcnt lgkmcnt(4)
	v_mfma_f32_32x32x16_bf16 v[128:143], v[226:229], v[116:119], v[128:143]
	ds_read_b128 v[222:225], v248 offset:27776
	v_add_f32_e32 v10, v10, v7
	v_cvt_pk_bf16_f32 v162, v6, v7
	v_add_f32_e32 v10, v10, v8
	v_add_f32_e32 v10, v10, v9
	v_cvt_pk_bf16_f32 v163, v8, v9
	s_waitcnt lgkmcnt(3)
	s_nop 0
	v_mfma_f32_32x32x16_bf16 v[32:47], v[176:179], v[160:163], v[32:47]
	ds_read_b128 v[226:229], v248 offset:27808
	v_exp_f32_e32 v0, v72
	v_exp_f32_e32 v1, v73
	v_exp_f32_e32 v2, v74
	s_waitcnt lgkmcnt(2)
	v_mfma_f32_32x32x16_bf16 v[16:31], v[180:183], v[160:163], v[16:31]
	ds_read_b128 v[176:179], v248 offset:34304
	v_exp_f32_e32 v3, v75
	v_add_f32_e32 v11, v0, v1
	v_cvt_pk_bf16_f32 v164, v0, v1
	v_add_f32_e32 v11, v11, v2
	s_waitcnt lgkmcnt(2)
	v_mfma_f32_32x32x16_bf16 v[128:143], v[222:225], v[120:123], v[128:143]
	ds_read_b64_tr_b16 v[180:181], v249 offset:18432
	ds_read_b64_tr_b16 v[182:183], v249 offset:19968
	v_add_f32_e32 v11, v11, v3
	v_cvt_pk_bf16_f32 v165, v2, v3
	v_exp_f32_e32 v6, v76
	v_exp_f32_e32 v7, v77
	s_waitcnt lgkmcnt(3)
	v_mfma_f32_32x32x16_bf16 v[128:143], v[226:229], v[124:127], v[128:143]
	ds_read_b64_tr_b16 v[222:223], v249 offset:18496
	ds_read_b64_tr_b16 v[224:225], v249 offset:20032
	v_exp_f32_e32 v8, v78
	v_exp_f32_e32 v9, v79
	v_add_f32_e32 v11, v11, v6
	v_add_f32_e32 v11, v11, v7
	s_waitcnt lgkmcnt(4)
	v_mfma_f32_32x32x16_bf16 v[144:159], v[176:179], v[104:107], v[48:63]
	ds_read_b128 v[226:229], v248 offset:34336
	v_cvt_pk_bf16_f32 v166, v6, v7
	v_add_f32_e32 v11, v11, v8
	v_add_f32_e32 v11, v11, v9
	v_cvt_pk_bf16_f32 v167, v8, v9
	s_waitcnt lgkmcnt(3)
	s_nop 0
	v_mfma_f32_32x32x16_bf16 v[32:47], v[180:183], v[164:167], v[32:47]
	ds_read_b128 v[176:179], v248 offset:34368
	v_exp_f32_e32 v0, v80
	v_exp_f32_e32 v1, v81
	v_exp_f32_e32 v2, v82
	s_waitcnt lgkmcnt(2)
	v_mfma_f32_32x32x16_bf16 v[16:31], v[222:225], v[164:167], v[16:31]
	ds_read_b128 v[180:183], v248 offset:34400
	v_exp_f32_e32 v3, v83
	v_add_f32_e32 v12, v0, v1
	v_cvt_pk_bf16_f32 v168, v0, v1
	v_add_f32_e32 v12, v12, v2
	s_waitcnt lgkmcnt(2)
	v_mfma_f32_32x32x16_bf16 v[144:159], v[226:229], v[108:111], v[144:159]
	ds_read_b64_tr_b16 v[222:223], v249 offset:21504
	ds_read_b64_tr_b16 v[224:225], v249 offset:23040
	v_add_f32_e32 v12, v12, v3
	v_cvt_pk_bf16_f32 v169, v2, v3
	v_exp_f32_e32 v6, v84
	v_exp_f32_e32 v7, v85
	s_waitcnt lgkmcnt(3)
	v_mfma_f32_32x32x16_bf16 v[144:159], v[176:179], v[112:115], v[144:159]
	ds_read_b64_tr_b16 v[226:227], v249 offset:21568
	ds_read_b64_tr_b16 v[228:229], v249 offset:23104
	v_exp_f32_e32 v8, v86
	v_exp_f32_e32 v9, v87
	v_add_f32_e32 v12, v12, v6
	v_add_f32_e32 v12, v12, v7
	s_waitcnt lgkmcnt(4)
	v_mfma_f32_32x32x16_bf16 v[144:159], v[180:183], v[116:119], v[144:159]
	ds_read_b128 v[176:179], v248 offset:34432
	v_cvt_pk_bf16_f32 v170, v6, v7
	v_add_f32_e32 v12, v12, v8
	v_add_f32_e32 v12, v12, v9
	v_cvt_pk_bf16_f32 v171, v8, v9
	s_waitcnt lgkmcnt(3)
	s_nop 0
	v_mfma_f32_32x32x16_bf16 v[32:47], v[222:225], v[168:171], v[32:47]
	ds_read_b128 v[180:183], v248 offset:34464
	v_exp_f32_e32 v0, v88
	v_exp_f32_e32 v1, v89
	v_exp_f32_e32 v2, v90
	v_exp_f32_e32 v3, v91
	s_waitcnt lgkmcnt(2)
	v_mfma_f32_32x32x16_bf16 v[16:31], v[226:229], v[168:171], v[16:31]
	ds_read_b64_tr_b16 v[222:223], v249 offset:24576
	ds_read_b64_tr_b16 v[224:225], v249 offset:26112
	v_add_f32_e32 v13, v0, v1
	v_cvt_pk_bf16_f32 v172, v0, v1
	v_add_f32_e32 v13, v13, v2
	v_add_f32_e32 v13, v13, v3
	v_cvt_pk_bf16_f32 v173, v2, v3
	s_waitcnt lgkmcnt(3)
	v_mfma_f32_32x32x16_bf16 v[144:159], v[176:179], v[120:123], v[144:159]
	ds_read_b64_tr_b16 v[226:227], v249 offset:24640
	ds_read_b64_tr_b16 v[228:229], v249 offset:26176
	v_exp_f32_e32 v6, v92
	v_exp_f32_e32 v7, v93
	v_exp_f32_e32 v8, v94
	v_exp_f32_e32 v9, v95
	v_add_f32_e32 v13, v13, v6
	s_waitcnt lgkmcnt(4)
; template <int MODE>
; DI void attn_item(const Params& p, int layer, int bh, int qb, char* lds) {
;     ...
; #pragma unroll
;           for (int st = 0; st < QS; ++st) {
;             bf16x8 kf = *(const bf16x8*)(Ks + (32 * sub + l32) * KSTR + ((mp * QS + st) * 16 + hh * 8) * 2);
;             if (st == 0) s[sub] = MFMA(kf, qf[mp][st], c0tile); else s[sub] = MFMA(kf, qf[mp][st], s[sub]);
;           }
;         }
;         __builtin_amdgcn_iglp_opt(1);
;         __builtin_amdgcn_s_setprio(0);
;         if (NMAP == 1) {
;           lds_s16x4* vb = (lds_s16x4*)(Ks + KBYTES + vlane);
; #pragma unroll
;           for (int i = 0; i < 16; ++i) {
;             const int sub_ = i >> 3, ks_ = (i >> 2) & 1, dt_ = (i >> 1) & 1, g_ = i & 1;
;             vpre[i] = __builtin_amdgcn_ds_read_tr16_b64_v4i16(vb + ((32 * sub_ + 16 * ks_ + 8 * g_) * VSTR + 64 * dt_) / 8);
;           }
;           __builtin_amdgcn_sched_barrier(0);
;         }
;         if (MODE != 0 && !far) {
; #pragma unroll
;           for (int sub = 0; sub < 2; ++sub)
; #pragma unroll
;             for (int r = 0; r < 16; ++r) s[sub][r] += brow[32 * sub + (r & 3) + 8 * (r >> 2)];
;         }
;         const bool first = (MODE != 2) && (t == 0) && (mp == 0);
;         auto rebase = [&]() {
;           float mx = fmaxf(fmaxf(s[0][0], s[0][1]), s[0][2]);
; #pragma unroll
;           for (int r = 3; r < 15; r += 2) mx = fmaxf(fmaxf(mx, s[0][r]), s[0][r + 1]);
;           mx = fmaxf(mx, s[0][15]);
; #pragma unroll
;           for (int r = 0; r < 16; r += 2) mx = fmaxf(fmaxf(mx, s[1][r]), s[1][r + 1]);
;           const float rm = xchg_max(mx);
;           float delta = first ? rm : fmaxf(rm, 0.f);
;           if (delta < -1e29f) delta = 0.f;
;           m += delta;
;           const float alpha = __builtin_amdgcn_exp2f(-delta);
; #pragma unroll
;           for (int mq = 0; mq < NMAP; ++mq) {
;             l[mq] *= alpha;
; #pragma unroll
;             for (int r = 0; r < 16; ++r) { O[mq][0][r] *= alpha; O[mq][1][r] *= alpha; }
;           }
; #pragma unroll
;           for (int r = 0; r < 16; ++r) { s[0][r] -= delta; s[1][r] -= delta; }
;           set_c0(cb - m);
;         };
;         float ps;
;         auto smpass = [&]() {
;           ps = 0.f;
; #pragma unroll
;           for (int sub = 0; sub < 2; ++sub)
; #pragma unroll
;             for (int ks = 0; ks < 2; ++ks)
; #pragma unroll
	v_mfma_f32_32x32x16_bf16 v[144:159], v[180:183], v[124:127], v[144:159]
	v_add_f32_e32 v13, v13, v7
	v_cvt_pk_bf16_f32 v174, v6, v7
	v_add_f32_e32 v13, v13, v8
	v_add_f32_e32 v13, v13, v9
	v_cvt_pk_bf16_f32 v175, v8, v9
	s_waitcnt lgkmcnt(2)
	s_nop 0
	v_mfma_f32_32x32x16_bf16 v[32:47], v[222:225], v[172:175], v[32:47]
	s_waitcnt lgkmcnt(0)
	v_mfma_f32_32x32x16_bf16 v[16:31], v[226:229], v[172:175], v[16:31]
	v_add_f32_e32 v10, v10, v11
	v_add_f32_e32 v12, v12, v13
	v_add_f32_e32 v10, v10, v12
	v_add_f32_e32 v192, v192, v10
	v_max_f32_e32 v193, v193, v10
	ds_read_b128 v[176:179], v200 offset:2048
	ds_read_b128 v[180:183], v200 offset:2080
	ds_read_b128 v[222:225], v200 offset:2112
	v_exp_f32_e32 v0, v128
	v_exp_f32_e32 v1, v129
	v_exp_f32_e32 v2, v130
	v_exp_f32_e32 v3, v131
	v_add_f32_e32 v10, v0, v1
	v_cvt_pk_bf16_f32 v160, v0, v1
	s_waitcnt lgkmcnt(2)
	v_mfma_f32_32x32x16_bf16 v[64:79], v[176:179], v[104:107], v[48:63]
	ds_read_b128 v[226:229], v200 offset:2144
	s_waitcnt lgkmcnt(2)
	v_mfma_f32_32x32x16_bf16 v[64:79], v[180:183], v[108:111], v[64:79]
	ds_read_b64_tr_b16 v[176:177], v249 offset:40960
	ds_read_b64_tr_b16 v[178:179], v249 offset:42496
	v_add_f32_e32 v10, v10, v2
	v_add_f32_e32 v10, v10, v3
	v_cvt_pk_bf16_f32 v161, v2, v3
	s_waitcnt lgkmcnt(3)
	v_mfma_f32_32x32x16_bf16 v[64:79], v[222:225], v[112:115], v[64:79]
	ds_read_b64_tr_b16 v[180:181], v249 offset:41024
	ds_read_b64_tr_b16 v[182:183], v249 offset:42560
	v_exp_f32_e32 v6, v132
	v_exp_f32_e32 v7, v133
	v_exp_f32_e32 v8, v134
	v_exp_f32_e32 v9, v135
	v_add_f32_e32 v10, v10, v6
	s_waitcnt lgkmcnt(4)
	v_mfma_f32_32x32x16_bf16 v[64:79], v[226:229], v[116:119], v[64:79]
	ds_read_b128 v[222:225], v200 offset:2176
	v_add_f32_e32 v10, v10, v7
	v_cvt_pk_bf16_f32 v162, v6, v7
	v_add_f32_e32 v10, v10, v8
	v_add_f32_e32 v10, v10, v9
	v_cvt_pk_bf16_f32 v163, v8, v9
	s_waitcnt lgkmcnt(3)
	s_nop 0
	v_mfma_f32_32x32x16_bf16 v[32:47], v[176:179], v[160:163], v[32:47]
	ds_read_b128 v[226:229], v200 offset:2208
	v_exp_f32_e32 v0, v136
	v_exp_f32_e32 v1, v137
	v_exp_f32_e32 v2, v138
	s_waitcnt lgkmcnt(2)
	v_mfma_f32_32x32x16_bf16 v[16:31], v[180:183], v[160:163], v[16:31]
	ds_read_b128 v[176:179], v200 offset:8704
	v_exp_f32_e32 v3, v139
	v_add_f32_e32 v11, v0, v1
	v_cvt_pk_bf16_f32 v164, v0, v1
	v_add_f32_e32 v11, v11, v2
	s_waitcnt lgkmcnt(2)
	v_mfma_f32_32x32x16_bf16 v[64:79], v[222:225], v[120:123], v[64:79]
	ds_read_b64_tr_b16 v[180:181], v249 offset:44032
	ds_read_b64_tr_b16 v[182:183], v249 offset:45568
	v_add_f32_e32 v11, v11, v3
	v_cvt_pk_bf16_f32 v165, v2, v3
	v_exp_f32_e32 v6, v140
	v_exp_f32_e32 v7, v141
	s_waitcnt lgkmcnt(3)
	v_mfma_f32_32x32x16_bf16 v[64:79], v[226:229], v[124:127], v[64:79]
	ds_read_b64_tr_b16 v[222:223], v249 offset:44096
	ds_read_b64_tr_b16 v[224:225], v249 offset:45632
	v_exp_f32_e32 v8, v142
	v_exp_f32_e32 v9, v143
	v_add_f32_e32 v11, v11, v6
	v_add_f32_e32 v11, v11, v7
	s_waitcnt lgkmcnt(4)
	v_mfma_f32_32x32x16_bf16 v[80:95], v[176:179], v[104:107], v[48:63]
	ds_read_b128 v[226:229], v200 offset:8736
	v_cvt_pk_bf16_f32 v166, v6, v7
	v_add_f32_e32 v11, v11, v8
	v_add_f32_e32 v11, v11, v9
	v_cvt_pk_bf16_f32 v167, v8, v9
	s_waitcnt lgkmcnt(3)
	s_nop 0
	v_mfma_f32_32x32x16_bf16 v[32:47], v[180:183], v[164:167], v[32:47]
	ds_read_b128 v[176:179], v200 offset:8768
	v_exp_f32_e32 v0, v144
	v_exp_f32_e32 v1, v145
	v_exp_f32_e32 v2, v146
	s_waitcnt lgkmcnt(2)
	v_mfma_f32_32x32x16_bf16 v[16:31], v[222:225], v[164:167], v[16:31]
	ds_read_b128 v[180:183], v200 offset:8800
	v_exp_f32_e32 v3, v147
	v_add_f32_e32 v12, v0, v1
	v_cvt_pk_bf16_f32 v168, v0, v1
	v_add_f32_e32 v12, v12, v2
	s_waitcnt lgkmcnt(2)
	v_mfma_f32_32x32x16_bf16 v[80:95], v[226:229], v[108:111], v[80:95]
	ds_read_b64_tr_b16 v[222:223], v249 offset:47104
	ds_read_b64_tr_b16 v[224:225], v249 offset:48640
	v_add_f32_e32 v12, v12, v3
	v_cvt_pk_bf16_f32 v169, v2, v3
	v_exp_f32_e32 v6, v148
	v_exp_f32_e32 v7, v149
	s_waitcnt lgkmcnt(3)
	v_mfma_f32_32x32x16_bf16 v[80:95], v[176:179], v[112:115], v[80:95]
	ds_read_b64_tr_b16 v[226:227], v249 offset:47168
	ds_read_b64_tr_b16 v[228:229], v249 offset:48704
	v_exp_f32_e32 v8, v150
	v_exp_f32_e32 v9, v151
	v_add_f32_e32 v12, v12, v6
	v_add_f32_e32 v12, v12, v7
	s_waitcnt lgkmcnt(4)
	v_mfma_f32_32x32x16_bf16 v[80:95], v[180:183], v[116:119], v[80:95]
	ds_read_b128 v[176:179], v200 offset:8832
	v_cvt_pk_bf16_f32 v170, v6, v7
	v_add_f32_e32 v12, v12, v8
	v_add_f32_e32 v12, v12, v9
	v_cvt_pk_bf16_f32 v171, v8, v9
	s_waitcnt lgkmcnt(3)
	s_nop 0
	v_mfma_f32_32x32x16_bf16 v[32:47], v[222:225], v[168:171], v[32:47]
	ds_read_b128 v[180:183], v200 offset:8864
	v_exp_f32_e32 v0, v152
	v_exp_f32_e32 v1, v153
	v_exp_f32_e32 v2, v154
	v_exp_f32_e32 v3, v155
	s_waitcnt lgkmcnt(2)
	v_mfma_f32_32x32x16_bf16 v[16:31], v[226:229], v[168:171], v[16:31]
	ds_read_b64_tr_b16 v[222:223], v249 offset:50176
	ds_read_b64_tr_b16 v[224:225], v249 offset:51712
	v_add_f32_e32 v13, v0, v1
	v_cvt_pk_bf16_f32 v172, v0, v1
	v_add_f32_e32 v13, v13, v2
	v_add_f32_e32 v13, v13, v3
	v_cvt_pk_bf16_f32 v173, v2, v3
	s_waitcnt lgkmcnt(3)
	v_mfma_f32_32x32x16_bf16 v[80:95], v[176:179], v[120:123], v[80:95]
	ds_read_b64_tr_b16 v[226:227], v249 offset:50240
	ds_read_b64_tr_b16 v[228:229], v249 offset:51776
	v_exp_f32_e32 v6, v156
	v_exp_f32_e32 v7, v157
	v_exp_f32_e32 v8, v158
	v_exp_f32_e32 v9, v159
	v_add_f32_e32 v13, v13, v6
	s_waitcnt lgkmcnt(4)
	v_mfma_f32_32x32x16_bf16 v[80:95], v[180:183], v[124:127], v[80:95]
	v_add_f32_e32 v13, v13, v7
	v_cvt_pk_bf16_f32 v174, v6, v7
	v_add_f32_e32 v13, v13, v8
	v_add_f32_e32 v13, v13, v9
	v_cvt_pk_bf16_f32 v175, v8, v9
	s_waitcnt lgkmcnt(2)
	s_nop 0
	v_mfma_f32_32x32x16_bf16 v[32:47], v[222:225], v[172:175], v[32:47]
	s_waitcnt lgkmcnt(0)
	v_mfma_f32_32x32x16_bf16 v[16:31], v[226:229], v[172:175], v[16:31]
	v_add_f32_e32 v10, v10, v11
	v_add_f32_e32 v12, v12, v13
	v_add_f32_e32 v10, v10, v12
	v_add_f32_e32 v192, v192, v10
	v_max_f32_e32 v193, v193, v10
	s_add_u32 s28, s28, 4
	s_cmpk_lt_u32 s28, 0x80
	s_waitcnt lgkmcnt(0)
	s_barrier
; DI unsigned pk2(float lo, float hi) { f32x2 v = {lo, hi}; b16x2 r = __builtin_convertvector(v, b16x2); return __builtin_bit_cast(unsigned, r); }
; DI float bflo(unsigned w) { return __uint_as_float(w << 16); }
; DI float bfhi(unsigned w) { return __uint_as_float(w & 0xffff0000u); }
; template <int MODE>
; DI void attn_item(const Params& p, int layer, int bh, int qb, char* lds) {
;     ...
;         if (!first && __any(!(ps <= PSLIM))) { rebase(); smpass(); }
;         l[mp] += ps;
;     ...
;   __syncthreads();
;   const size_t trow = (size_t)b * S + q0w + l32;
;   const u16* grow = (const u16*)(p.ws + OFF_H) + trow * DIN + C_GATE + ocol;
;   u16* orow = (u16*)(p.ws + OFF_OB) + trow * DM + ocol;
;   float inv0 = 1.f / xchg_sum(l[0]);
;   if (MODE == 1) {
;     const float* lm = (const float*)(p.ws + OFF_LAM);
;     const float lam = lm[layer], post = lm[4 + layer];
;     const float inv1 = lam / xchg_sum(l[1]);
;     float ss = 0.f;
; #pragma unroll
;     for (int dt = 0; dt < 2; ++dt)
; #pragma unroll
;       for (int r = 0; r < 16; ++r) { float v = O[0][dt][r] * inv0 - O[NMAP - 1][dt][r] * inv1; O[0][dt][r] = v; ss += v * v; }
;     ss = xchg_sum(ss);
;     inv0 = rsqrtf(ss * (1.f / 64.f) + 1e-6f) * post;
;   }
; #pragma unroll
;   for (int dt = 0; dt < 2; ++dt)
; #pragma unroll
;     for (int g = 0; g < 4; ++g) {
;       const int d = 32 * dt + 8 * g + 4 * hh;
;       u32x2 gw = *(const u32x2*)(grow + d);
;       float v0 = O[0][dt][4 * g + 0] * inv0, v1 = O[0][dt][4 * g + 1] * inv0, v2 = O[0][dt][4 * g + 2] * inv0, v3 = O[0][dt][4 * g + 3] * inv0;
;       if (MODE == 1) { const float* sl = p.subln + layer * 64 + d; v0 *= sl[0]; v1 *= sl[1]; v2 *= sl[2]; v3 *= sl[3]; }
;       v0 *= bflo(gw[0]); v1 *= bfhi(gw[0]); v2 *= bflo(gw[1]); v3 *= bfhi(gw[1]);
;       u32x2 ow = {pk2(v0, v1), pk2(v2, v3)};
;     ...
;       if (MODE == PROBE_ZERO_MODE) { ow[0] = 0u; ow[1] = 0u; }
;     ...
;       *(u32x2*)(orow + d) = ow;
	s_cbranch_scc1 .Lmla_loop
	s_waitcnt vmcnt(0)
	s_lshl_b64 s[6:7], s[10:11], 13
	v_ashrrev_i32_e32 v187, 31, v186
	v_lshl_add_u64 v[0:1], s[6:7], 0, v[186:187]
	v_or_b32_e32 v0, v0, v204
	v_mov_b32_e32 v2, s34
	v_mov_b32_e32 v3, s35
	v_mad_u64_u32 v[2:3], s[6:7], v0, s64, v[2:3]
	v_mad_i32_i24 v3, v1, s64, v3
	s_lshl_b32 s4, s52, 7
	v_lshl_add_u32 v12, v206, 1, s4
	v_mov_b32_e32 v13, 0
	v_lshl_add_u64 v[6:7], v[2:3], 0, v[12:13]
	s_mov_b64 s[6:7], 0x6058ec0
	v_lshl_add_u64 v[6:7], v[6:7], 0, s[6:7]
	global_load_dwordx2 v[64:65], v[6:7], off offset:0
	global_load_dwordx2 v[66:67], v[6:7], off offset:16
	global_load_dwordx2 v[68:69], v[6:7], off offset:32
	global_load_dwordx2 v[70:71], v[6:7], off offset:48
	global_load_dwordx2 v[72:73], v[6:7], off offset:64
	global_load_dwordx2 v[74:75], v[6:7], off offset:80
	global_load_dwordx2 v[76:77], v[6:7], off offset:96
	global_load_dwordx2 v[78:79], v[6:7], off offset:112
	v_readlane_b32 s6, v254, 49
	v_readlane_b32 s7, v254, 50
	v_lshlrev_b64 v[0:1], 11, v[0:1]
	s_nop 0
	v_lshl_add_u64 v[0:1], s[6:7], 0, v[0:1]
	v_lshl_add_u64 v[8:9], v[0:1], 0, v[12:13]
	v_cmp_nge_f32_e32 vcc, s94, v193
	s_nop 0
	s_cmp_lg_u64 vcc, 0
	s_cselect_b32 s24, 1, 0
	v_mov_b32_e32 v196, s24
	v_lshrrev_b32_e32 v197, 6, v184
	v_lshlrev_b32_e32 v197, 2, v197
	ds_write_b32 v197, v196 offset:0
	s_waitcnt lgkmcnt(0)
	s_barrier
	v_mov_b32_e32 v197, 0
	ds_read_b128 v[176:179], v197 offset:0
	ds_read_b128 v[180:183], v197 offset:16
	v_mov_b32_e32 v2, v192
	s_nop 1
	v_permlane32_swap_b32_e32 v192, v2
	v_add_f32_e32 v2, v192, v2
	v_div_scale_f32 v3, s[4:5], v2, v2, 1.0
	v_rcp_f32_e32 v4, v3
	s_nop 0
	v_fma_f32 v10, -v3, v4, 1.0
	v_fmac_f32_e32 v4, v10, v4
	v_div_scale_f32 v10, vcc, 1.0, v2, 1.0
	v_mul_f32_e32 v11, v10, v4
	v_fma_f32 v12, -v3, v11, v10
	v_fmac_f32_e32 v11, v12, v4
	v_fma_f32 v3, -v3, v11, v10
	s_nop 1
	v_div_fmas_f32 v3, v3, v4, v11
	v_div_fixup_f32 v2, v3, v2, 1.0
	s_waitcnt lgkmcnt(0)
	v_or3_b32 v196, v176, v177, v178
	v_or3_b32 v196, v196, v179, v180
	v_or3_b32 v196, v196, v181, v182
	v_or_b32_e32 v196, v196, v183
	s_nop 0
	v_readfirstlane_b32 s24, v196
	s_barrier
	s_cmp_lg_u32 s24, 0
	s_cbranch_scc1 .Lmla_slow
	s_waitcnt vmcnt(0)
	v_mul_f32_e32 v32, v32, v2
	v_mul_f32_e32 v33, v33, v2
	v_mul_f32_e32 v34, v34, v2
	v_mul_f32_e32 v35, v35, v2
	v_lshlrev_b32_e32 v196, 16, v64
	v_and_b32_e32 v197, 0xffff0000, v64
	v_mul_f32_e32 v32, v32, v196
	v_mul_f32_e32 v33, v33, v197
	v_lshlrev_b32_e32 v196, 16, v65
	v_and_b32_e32 v197, 0xffff0000, v65
	v_mul_f32_e32 v34, v34, v196
	v_mul_f32_e32 v35, v35, v197
	v_cvt_pk_bf16_f32 v32, v32, v33
	v_cvt_pk_bf16_f32 v33, v34, v35
	global_store_dwordx2 v[8:9], v[32:33], off offset:0
	v_mul_f32_e32 v36, v36, v2
	v_mul_f32_e32 v37, v37, v2
	v_mul_f32_e32 v38, v38, v2
	v_mul_f32_e32 v39, v39, v2
	v_lshlrev_b32_e32 v196, 16, v66
	v_and_b32_e32 v197, 0xffff0000, v66
	v_mul_f32_e32 v36, v36, v196
	v_mul_f32_e32 v37, v37, v197
	v_lshlrev_b32_e32 v196, 16, v67
	v_and_b32_e32 v197, 0xffff0000, v67
	v_mul_f32_e32 v38, v38, v196
	v_mul_f32_e32 v39, v39, v197
	v_cvt_pk_bf16_f32 v36, v36, v37
	v_cvt_pk_bf16_f32 v37, v38, v39
	global_store_dwordx2 v[8:9], v[36:37], off offset:16
	v_mul_f32_e32 v40, v40, v2
	v_mul_f32_e32 v41, v41, v2
	v_mul_f32_e32 v42, v42, v2
	v_mul_f32_e32 v43, v43, v2
	v_lshlrev_b32_e32 v196, 16, v68
	v_and_b32_e32 v197, 0xffff0000, v68
	v_mul_f32_e32 v40, v40, v196
	v_mul_f32_e32 v41, v41, v197
	v_lshlrev_b32_e32 v196, 16, v69
	v_and_b32_e32 v197, 0xffff0000, v69
	v_mul_f32_e32 v42, v42, v196
	v_mul_f32_e32 v43, v43, v197
	v_cvt_pk_bf16_f32 v40, v40, v41
	v_cvt_pk_bf16_f32 v41, v42, v43
	global_store_dwordx2 v[8:9], v[40:41], off offset:32
	v_mul_f32_e32 v44, v44, v2
	v_mul_f32_e32 v45, v45, v2
	v_mul_f32_e32 v46, v46, v2
	v_mul_f32_e32 v47, v47, v2
	v_lshlrev_b32_e32 v196, 16, v70
	v_and_b32_e32 v197, 0xffff0000, v70
	v_mul_f32_e32 v44, v44, v196
	v_mul_f32_e32 v45, v45, v197
	v_lshlrev_b32_e32 v196, 16, v71
	v_and_b32_e32 v197, 0xffff0000, v71
	v_mul_f32_e32 v46, v46, v196
	v_mul_f32_e32 v47, v47, v197
	v_cvt_pk_bf16_f32 v44, v44, v45
	v_cvt_pk_bf16_f32 v45, v46, v47
	global_store_dwordx2 v[8:9], v[44:45], off offset:48
	v_mul_f32_e32 v16, v16, v2
	v_mul_f32_e32 v17, v17, v2
	v_mul_f32_e32 v18, v18, v2
	v_mul_f32_e32 v19, v19, v2
	v_lshlrev_b32_e32 v196, 16, v72
	v_and_b32_e32 v197, 0xffff0000, v72
	v_mul_f32_e32 v16, v16, v196
	v_mul_f32_e32 v17, v17, v197
	v_lshlrev_b32_e32 v196, 16, v73
	v_and_b32_e32 v197, 0xffff0000, v73
	v_mul_f32_e32 v18, v18, v196
	v_mul_f32_e32 v19, v19, v197
	v_cvt_pk_bf16_f32 v16, v16, v17
	v_cvt_pk_bf16_f32 v17, v18, v19
	global_store_dwordx2 v[8:9], v[16:17], off offset:64
	v_mul_f32_e32 v20, v20, v2
	v_mul_f32_e32 v21, v21, v2
	v_mul_f32_e32 v22, v22, v2
	v_mul_f32_e32 v23, v23, v2
	v_lshlrev_b32_e32 v196, 16, v74
	v_and_b32_e32 v197, 0xffff0000, v74
	v_mul_f32_e32 v20, v20, v196
	v_mul_f32_e32 v21, v21, v197
	v_lshlrev_b32_e32 v196, 16, v75
	v_and_b32_e32 v197, 0xffff0000, v75
	v_mul_f32_e32 v22, v22, v196
	v_mul_f32_e32 v23, v23, v197
	v_cvt_pk_bf16_f32 v20, v20, v21
	v_cvt_pk_bf16_f32 v21, v22, v23
	global_store_dwordx2 v[8:9], v[20:21], off offset:80
	v_mul_f32_e32 v24, v24, v2
	v_mul_f32_e32 v25, v25, v2
	v_mul_f32_e32 v26, v26, v2
	v_mul_f32_e32 v27, v27, v2
	v_lshlrev_b32_e32 v196, 16, v76
	v_and_b32_e32 v197, 0xffff0000, v76
	v_mul_f32_e32 v24, v24, v196
	v_mul_f32_e32 v25, v25, v197
	v_lshlrev_b32_e32 v196, 16, v77
	v_and_b32_e32 v197, 0xffff0000, v77
	v_mul_f32_e32 v26, v26, v196
	v_mul_f32_e32 v27, v27, v197
	v_cvt_pk_bf16_f32 v24, v24, v25
	v_cvt_pk_bf16_f32 v25, v26, v27
	global_store_dwordx2 v[8:9], v[24:25], off offset:96
	v_mul_f32_e32 v28, v28, v2
	v_mul_f32_e32 v29, v29, v2
	v_mul_f32_e32 v30, v30, v2
	v_mul_f32_e32 v31, v31, v2
	v_lshlrev_b32_e32 v196, 16, v78
	v_and_b32_e32 v197, 0xffff0000, v78
	v_mul_f32_e32 v28, v28, v196
	v_mul_f32_e32 v29, v29, v197
	v_lshlrev_b32_e32 v196, 16, v79
	v_and_b32_e32 v197, 0xffff0000, v79
	v_mul_f32_e32 v30, v30, v196
	v_mul_f32_e32 v31, v31, v197
	v_cvt_pk_bf16_f32 v28, v28, v29
	v_cvt_pk_bf16_f32 v29, v30, v31
	global_store_dwordx2 v[8:9], v[28:29], off offset:112
	s_branch .LBB0_321
